# v77 + grid barrier leader path: no wait between the release atomic and the L2 invalidate, unused per-XCD release atomic dropped (releasing leader leaves the barrier about one atomic round trip sooner)
# speedup vs baseline: 1.0026x; 1.0004x over previous
; __device__ __forceinline__ unsigned xb_ld(unsigned* p)              { return __hip_atomic_load(p, __ATOMIC_RELAXED, __HIP_MEMORY_SCOPE_AGENT); }
; __device__ __forceinline__ unsigned xb_add(unsigned* p, unsigned v) { return __hip_atomic_fetch_add(p, v, __ATOMIC_RELAXED, __HIP_MEMORY_SCOPE_AGENT); }
; #define XB_SPIN(cond, bar) do { unsigned _sp = 0; while (cond) { __builtin_amdgcn_s_sleep(1); \
;     if ((++_sp & 255u) == 0u) { if (xb_ld(&(bar)[XB_TMO])) break; if (_sp > XB_SPIN_CAP) { atomicAdd(&(bar)[XB_TMO], 1u); break; } } } } while (0)
; __device__ __forceinline__ void xcd_barrier(const XcdBarrier& b) {
;     ...
;             if (og + 1u == (tg + 1u) * nx) xb_add(&bar[XB_TOPGEN], 1u);
;             else XB_SPIN(xb_ld(&bar[XB_TOPGEN]) == tg, bar);
;             __builtin_amdgcn_fence(__ATOMIC_ACQUIRE, "agent");
;             xb_add(&bar[XB_XGEN(b.x)], 1u);
.LBB0_174:
	s_or_b64 exec, exec, s[14:15]
	s_mov_b64 s[14:15], exec
	v_mbcnt_lo_u32_b32 v0, s14, 0
	v_mbcnt_hi_u32_b32 v0, s15, v0
	v_cmp_eq_u32_e32 vcc, 0, v0
	buffer_inv sc1
	s_and_saveexec_b64 s[20:21], vcc
	s_cbranch_execz .LBB0_176
	s_bcnt1_i32_b64 s2, s[14:15]
	v_mov_b32_e32 v0, s2
	v_readlane_b32 s2, v253, 61
	v_readlane_b32 s3, v253, 62
	s_nop 4

; __device__ __forceinline__ unsigned xb_ld(unsigned* p)              { return __hip_atomic_load(p, __ATOMIC_RELAXED, __HIP_MEMORY_SCOPE_AGENT); }
; __device__ __forceinline__ unsigned xb_add(unsigned* p, unsigned v) { return __hip_atomic_fetch_add(p, v, __ATOMIC_RELAXED, __HIP_MEMORY_SCOPE_AGENT); }
; #define XB_SPIN(cond, bar) do { unsigned _sp = 0; while (cond) { __builtin_amdgcn_s_sleep(1); \
;     if ((++_sp & 255u) == 0u) { if (xb_ld(&(bar)[XB_TMO])) break; if (_sp > XB_SPIN_CAP) { atomicAdd(&(bar)[XB_TMO], 1u); break; } } } } while (0)
; __device__ __forceinline__ void xcd_barrier(const XcdBarrier& b) {
;     ...
;             if (og + 1u == (tg + 1u) * nx) xb_add(&bar[XB_TOPGEN], 1u);
;             else XB_SPIN(xb_ld(&bar[XB_TOPGEN]) == tg, bar);
;             __builtin_amdgcn_fence(__ATOMIC_ACQUIRE, "agent");
;             xb_add(&bar[XB_XGEN(b.x)], 1u);
.LBB0_439:
	s_or_b64 exec, exec, s[10:11]
	s_mov_b64 s[10:11], exec
	v_mbcnt_lo_u32_b32 v0, s10, 0
	v_mbcnt_hi_u32_b32 v0, s11, v0
	v_cmp_eq_u32_e32 vcc, 0, v0
	buffer_inv sc1
	s_and_saveexec_b64 s[14:15], vcc
	s_cbranch_execz .LBB0_441
	s_bcnt1_i32_b64 s2, s[10:11]
	v_mov_b32_e32 v0, s2
	v_readlane_b32 s2, v253, 61
	v_readlane_b32 s3, v253, 62
	s_nop 4

; __device__ __forceinline__ unsigned xb_ld(unsigned* p)              { return __hip_atomic_load(p, __ATOMIC_RELAXED, __HIP_MEMORY_SCOPE_AGENT); }
; __device__ __forceinline__ unsigned xb_add(unsigned* p, unsigned v) { return __hip_atomic_fetch_add(p, v, __ATOMIC_RELAXED, __HIP_MEMORY_SCOPE_AGENT); }
; #define XB_SPIN(cond, bar) do { unsigned _sp = 0; while (cond) { __builtin_amdgcn_s_sleep(1); \
;     if ((++_sp & 255u) == 0u) { if (xb_ld(&(bar)[XB_TMO])) break; if (_sp > XB_SPIN_CAP) { atomicAdd(&(bar)[XB_TMO], 1u); break; } } } } while (0)
; __device__ __forceinline__ void xcd_barrier(const XcdBarrier& b) {
;     ...
;             if (og + 1u == (tg + 1u) * nx) xb_add(&bar[XB_TOPGEN], 1u);
;             else XB_SPIN(xb_ld(&bar[XB_TOPGEN]) == tg, bar);
;             __builtin_amdgcn_fence(__ATOMIC_ACQUIRE, "agent");
;             xb_add(&bar[XB_XGEN(b.x)], 1u);
.LBB0_660:
	s_or_b64 exec, exec, s[8:9]
	s_mov_b64 s[8:9], exec
	v_mbcnt_lo_u32_b32 v0, s8, 0
	v_mbcnt_hi_u32_b32 v0, s9, v0
	v_cmp_eq_u32_e32 vcc, 0, v0
	buffer_inv sc1
	s_and_saveexec_b64 s[10:11], vcc
	s_cbranch_execz .LBB0_662
	s_bcnt1_i32_b64 s2, s[8:9]
	v_mov_b32_e32 v0, s2
	v_readlane_b32 s2, v253, 61
	v_readlane_b32 s3, v253, 62
	s_nop 4
